# ladder-1 pipeline depth 3 with saddr+offset32 addressing (vs depth 2)
# baseline (speedup 1.0000x reference)
; #define LAS __attribute__((address_space(3)))
;     __device__ __forceinline__ void operator()(f32x4 (&acc)[2][2][4][2], const Unit& u, int wr, int wc, int fr, int fq) const {
;         const LAS float* S = (const LAS float*)(lds + EN_S);
;         const int col0 = u.pn * 256 + wc * 32 + 8 * fq;
;         exchange(acc, u, 0, wr, wc, fr, fq);
; #pragma unroll
;         for (int ai = 0; ai < 2; ++ai)
; #pragma unroll
;             for (int m = 0; m < 4; ++m) { const int rl = ai * 128 + wr * 64 + m * 16 + fr; const float r1 = S[rl]; const size_t off = (size_t)(u.pm * 256 + rl) * DM + col0;
; #pragma unroll
;                 for (int bj = 0; bj < 2; ++bj) { const f32x4 xa = *(const f32x4*)(xin + off + bj * 128), xb = *(const f32x4*)(xin + off + bj * 128 + 4);
;                     const f32x4 ga = *(const f32x4*)(gpost + col0 + bj * 128), gb = *(const f32x4*)(gpost + col0 + bj * 128 + 4);
;                     const f32x4 v0 = xa + acc[ai][bj][m][0] * r1 * ga, v1 = xb + acc[ai][bj][m][1] * r1 * gb;
;                     *(f32x4*)(xout + off + bj * 128) = v0; *(f32x4*)(xout + off + bj * 128 + 4) = v1; acc[ai][bj][m][0] = v0; acc[ai][bj][m][1] = v1; }
;                 asm volatile("" ::: "memory"); }
.LBB0_103:
	s_or_b64 exec, exec, s[84:85]
	s_lshl_b32 s54, s82, 8
	v_add_u32_e32 v144, s54, v170
	v_lshl_or_b32 v142, s78, 8, v190
	v_ashrrev_i32_e32 v145, 31, v144
	v_ashrrev_i32_e32 v143, 31, v142
	v_lshlrev_b64 v[146:147], 12, v[144:145]
	v_lshl_add_u64 v[146:147], s[34:35], 0, v[146:147]
	v_lshlrev_b64 v[158:159], 2, v[142:143]
	v_lshl_add_u64 v[160:161], v[146:147], 0, v[158:159]
	v_lshl_add_u64 v[154:155], s[52:53], 0, v[158:159]
	global_load_dwordx4 v[218:221], v[154:155], off
	global_load_dwordx4 v[222:225], v[154:155], off offset:16
	global_load_dwordx4 v[226:229], v[154:155], off offset:512
	global_load_dwordx4 v[230:233], v[154:155], off offset:528
	s_waitcnt lgkmcnt(0)
	s_barrier
	s_andn2_b64 vcc, exec, s[62:63]
	v_lshl_add_u32 v154, v144, 12, v158
	ds_read_b32 v250, v182
	global_load_dwordx4 v[202:205], v154, s[34:35] offset:16
	global_load_dwordx4 v[206:209], v154, s[34:35]
	global_load_dwordx4 v[210:213], v154, s[34:35] offset:528
	global_load_dwordx4 v[214:217], v154, s[34:35] offset:512
	v_add_u32_e32 v157, s54, v173
	v_lshl_add_u32 v155, v157, 12, v158
	ds_read_b32 v192, v183
	global_load_dwordx4 v[234:237], v155, s[34:35] offset:16
	global_load_dwordx4 v[238:241], v155, s[34:35]
	global_load_dwordx4 v[242:245], v155, s[34:35] offset:528
	global_load_dwordx4 v[246:249], v155, s[34:35] offset:512
	v_add_u32_e32 v157, s54, v174
	v_lshl_add_u32 v156, v157, 12, v158
	ds_read_b32 v196, v184
	global_load_dwordx4 v[146:149], v156, s[34:35] offset:16
	global_load_dwordx4 v[150:153], v156, s[34:35]
	global_load_dwordx4 v[162:165], v156, s[34:35] offset:528
	global_load_dwordx4 v[166:169], v156, s[34:35] offset:512
	s_waitcnt lgkmcnt(2)
	v_pk_mul_f32 v[50:51], v[50:51], v[250:251] op_sel_hi:[1,0]
	v_pk_mul_f32 v[52:53], v[52:53], v[250:251] op_sel_hi:[1,0]
	v_pk_mul_f32 v[54:55], v[54:55], v[250:251] op_sel_hi:[1,0]
	v_pk_mul_f32 v[56:57], v[56:57], v[250:251] op_sel_hi:[1,0]
	v_pk_mul_f32 v[62:63], v[62:63], v[250:251] op_sel_hi:[1,0]
	v_pk_mul_f32 v[64:65], v[64:65], v[250:251] op_sel_hi:[1,0]
	v_pk_mul_f32 v[58:59], v[58:59], v[250:251] op_sel_hi:[1,0]
	v_pk_mul_f32 v[60:61], v[60:61], v[250:251] op_sel_hi:[1,0]
	s_waitcnt vmcnt(8)
	v_pk_fma_f32 v[54:55], v[54:55], v[222:223], v[202:203]
	v_pk_fma_f32 v[56:57], v[56:57], v[224:225], v[204:205]
	v_pk_fma_f32 v[50:51], v[50:51], v[218:219], v[206:207]
	v_pk_fma_f32 v[52:53], v[52:53], v[220:221], v[208:209]
	v_pk_fma_f32 v[58:59], v[58:59], v[230:231], v[210:211]
	v_pk_fma_f32 v[60:61], v[60:61], v[232:233], v[212:213]
	v_pk_fma_f32 v[62:63], v[62:63], v[226:227], v[214:215]
	v_pk_fma_f32 v[64:65], v[64:65], v[228:229], v[216:217]
	global_store_dwordx4 v154, v[50:53], s[34:35]
	global_store_dwordx4 v154, v[54:57], s[34:35] offset:16
	global_store_dwordx4 v154, v[62:65], s[34:35] offset:512
	global_store_dwordx4 v154, v[58:61], s[34:35] offset:528
	v_add_u32_e32 v157, s54, v175
	v_lshl_add_u32 v154, v157, 12, v158
	ds_read_b32 v250, v185
	global_load_dwordx4 v[202:205], v154, s[34:35] offset:16
	global_load_dwordx4 v[206:209], v154, s[34:35]
	global_load_dwordx4 v[210:213], v154, s[34:35] offset:528
	global_load_dwordx4 v[214:217], v154, s[34:35] offset:512
	s_waitcnt lgkmcnt(2)
	v_pk_mul_f32 v[74:75], v[74:75], v[192:193] op_sel_hi:[1,0]
	v_pk_mul_f32 v[76:77], v[76:77], v[192:193] op_sel_hi:[1,0]
	v_pk_mul_f32 v[78:79], v[78:79], v[192:193] op_sel_hi:[1,0]
	v_pk_mul_f32 v[80:81], v[80:81], v[192:193] op_sel_hi:[1,0]
	v_pk_mul_f32 v[94:95], v[94:95], v[192:193] op_sel_hi:[1,0]
	v_pk_mul_f32 v[96:97], v[96:97], v[192:193] op_sel_hi:[1,0]
	v_pk_mul_f32 v[90:91], v[90:91], v[192:193] op_sel_hi:[1,0]
	v_pk_mul_f32 v[92:93], v[92:93], v[192:193] op_sel_hi:[1,0]
	s_waitcnt vmcnt(12)
	v_pk_fma_f32 v[78:79], v[78:79], v[222:223], v[234:235]
	v_pk_fma_f32 v[80:81], v[80:81], v[224:225], v[236:237]
	v_pk_fma_f32 v[74:75], v[74:75], v[218:219], v[238:239]
	v_pk_fma_f32 v[76:77], v[76:77], v[220:221], v[240:241]
	v_pk_fma_f32 v[90:91], v[90:91], v[230:231], v[242:243]
	v_pk_fma_f32 v[92:93], v[92:93], v[232:233], v[244:245]
	v_pk_fma_f32 v[94:95], v[94:95], v[226:227], v[246:247]
	v_pk_fma_f32 v[96:97], v[96:97], v[228:229], v[248:249]
	global_store_dwordx4 v155, v[74:77], s[34:35]
	global_store_dwordx4 v155, v[78:81], s[34:35] offset:16
	global_store_dwordx4 v155, v[94:97], s[34:35] offset:512
	global_store_dwordx4 v155, v[90:93], s[34:35] offset:528
	v_add_u32_e32 v157, s54, v176
	v_lshl_add_u32 v155, v157, 12, v158
	ds_read_b32 v192, v186
	global_load_dwordx4 v[234:237], v155, s[34:35] offset:16
	global_load_dwordx4 v[238:241], v155, s[34:35]
	global_load_dwordx4 v[242:245], v155, s[34:35] offset:528
	global_load_dwordx4 v[246:249], v155, s[34:35] offset:512
	s_waitcnt lgkmcnt(2)
	v_pk_mul_f32 v[98:99], v[98:99], v[196:197] op_sel_hi:[1,0]
	v_pk_mul_f32 v[100:101], v[100:101], v[196:197] op_sel_hi:[1,0]
	v_pk_mul_f32 v[102:103], v[102:103], v[196:197] op_sel_hi:[1,0]
	v_pk_mul_f32 v[104:105], v[104:105], v[196:197] op_sel_hi:[1,0]
	v_pk_mul_f32 v[118:119], v[118:119], v[196:197] op_sel_hi:[1,0]
	v_pk_mul_f32 v[120:121], v[120:121], v[196:197] op_sel_hi:[1,0]
	v_pk_mul_f32 v[114:115], v[114:115], v[196:197] op_sel_hi:[1,0]
	v_pk_mul_f32 v[116:117], v[116:117], v[196:197] op_sel_hi:[1,0]
	s_waitcnt vmcnt(16)
;     __device__ __forceinline__ void operator()(f32x4 (&acc)[2][2][4][2], const Unit& u, int wr, int wc, int fr, int fq) const {
;     ...
; #pragma unroll
;         for (int ai = 0; ai < 2; ++ai)
; #pragma unroll
;             for (int m = 0; m < 4; ++m) { const int rl = ai * 128 + wr * 64 + m * 16 + fr; const float r1 = S[rl]; const size_t off = (size_t)(u.pm * 256 + rl) * DM + col0;
; #pragma unroll
;                 for (int bj = 0; bj < 2; ++bj) { const f32x4 xa = *(const f32x4*)(xin + off + bj * 128), xb = *(const f32x4*)(xin + off + bj * 128 + 4);
;                     const f32x4 ga = *(const f32x4*)(gpost + col0 + bj * 128), gb = *(const f32x4*)(gpost + col0 + bj * 128 + 4);
;                     const f32x4 v0 = xa + acc[ai][bj][m][0] * r1 * ga, v1 = xb + acc[ai][bj][m][1] * r1 * gb;
;                     *(f32x4*)(xout + off + bj * 128) = v0; *(f32x4*)(xout + off + bj * 128 + 4) = v1; acc[ai][bj][m][0] = v0; acc[ai][bj][m][1] = v1; }
;                 asm volatile("" ::: "memory"); }
	v_pk_fma_f32 v[102:103], v[102:103], v[222:223], v[146:147]
	v_pk_fma_f32 v[104:105], v[104:105], v[224:225], v[148:149]
	v_pk_fma_f32 v[98:99], v[98:99], v[218:219], v[150:151]
	v_pk_fma_f32 v[100:101], v[100:101], v[220:221], v[152:153]
	v_pk_fma_f32 v[114:115], v[114:115], v[230:231], v[162:163]
	v_pk_fma_f32 v[116:117], v[116:117], v[232:233], v[164:165]
	v_pk_fma_f32 v[118:119], v[118:119], v[226:227], v[166:167]
	v_pk_fma_f32 v[120:121], v[120:121], v[228:229], v[168:169]
	global_store_dwordx4 v156, v[98:101], s[34:35]
	global_store_dwordx4 v156, v[102:105], s[34:35] offset:16
	global_store_dwordx4 v156, v[118:121], s[34:35] offset:512
	global_store_dwordx4 v156, v[114:117], s[34:35] offset:528
	v_add_u32_e32 v157, s54, v177
	v_lshl_add_u32 v156, v157, 12, v158
	ds_read_b32 v196, v187
	global_load_dwordx4 v[146:149], v156, s[34:35] offset:16
	global_load_dwordx4 v[150:153], v156, s[34:35]
	global_load_dwordx4 v[162:165], v156, s[34:35] offset:528
	global_load_dwordx4 v[166:169], v156, s[34:35] offset:512
	s_waitcnt lgkmcnt(2)
	v_pk_mul_f32 v[126:127], v[126:127], v[250:251] op_sel_hi:[1,0]
	v_pk_mul_f32 v[128:129], v[128:129], v[250:251] op_sel_hi:[1,0]
	v_pk_mul_f32 v[122:123], v[122:123], v[250:251] op_sel_hi:[1,0]
	v_pk_mul_f32 v[124:125], v[124:125], v[250:251] op_sel_hi:[1,0]
	v_pk_mul_f32 v[110:111], v[110:111], v[250:251] op_sel_hi:[1,0]
	v_pk_mul_f32 v[112:113], v[112:113], v[250:251] op_sel_hi:[1,0]
	v_pk_mul_f32 v[106:107], v[106:107], v[250:251] op_sel_hi:[1,0]
	v_pk_mul_f32 v[108:109], v[108:109], v[250:251] op_sel_hi:[1,0]
	s_waitcnt vmcnt(16)
	v_pk_fma_f32 v[122:123], v[122:123], v[222:223], v[202:203]
	v_pk_fma_f32 v[124:125], v[124:125], v[224:225], v[204:205]
	v_pk_fma_f32 v[126:127], v[126:127], v[218:219], v[206:207]
	v_pk_fma_f32 v[128:129], v[128:129], v[220:221], v[208:209]
	v_pk_fma_f32 v[106:107], v[106:107], v[230:231], v[210:211]
	v_pk_fma_f32 v[108:109], v[108:109], v[232:233], v[212:213]
	v_pk_fma_f32 v[110:111], v[110:111], v[226:227], v[214:215]
	v_pk_fma_f32 v[112:113], v[112:113], v[228:229], v[216:217]
	global_store_dwordx4 v154, v[126:129], s[34:35]
	global_store_dwordx4 v154, v[122:125], s[34:35] offset:16
	global_store_dwordx4 v154, v[110:113], s[34:35] offset:512
	global_store_dwordx4 v154, v[106:109], s[34:35] offset:528
	v_add_u32_e32 v157, s54, v178
	v_lshl_add_u32 v154, v157, 12, v158
	ds_read_b32 v250, v188
	global_load_dwordx4 v[202:205], v154, s[34:35] offset:16
	global_load_dwordx4 v[206:209], v154, s[34:35]
	global_load_dwordx4 v[210:213], v154, s[34:35] offset:528
	global_load_dwordx4 v[214:217], v154, s[34:35] offset:512
	s_waitcnt lgkmcnt(2)
	v_pk_mul_f32 v[86:87], v[86:87], v[192:193] op_sel_hi:[1,0]
	v_pk_mul_f32 v[88:89], v[88:89], v[192:193] op_sel_hi:[1,0]
	v_pk_mul_f32 v[82:83], v[82:83], v[192:193] op_sel_hi:[1,0]
	v_pk_mul_f32 v[84:85], v[84:85], v[192:193] op_sel_hi:[1,0]
	v_pk_mul_f32 v[70:71], v[70:71], v[192:193] op_sel_hi:[1,0]
	v_pk_mul_f32 v[72:73], v[72:73], v[192:193] op_sel_hi:[1,0]
	v_pk_mul_f32 v[66:67], v[66:67], v[192:193] op_sel_hi:[1,0]
	v_pk_mul_f32 v[68:69], v[68:69], v[192:193] op_sel_hi:[1,0]
	s_waitcnt vmcnt(16)
	v_pk_fma_f32 v[82:83], v[82:83], v[222:223], v[234:235]
	v_pk_fma_f32 v[84:85], v[84:85], v[224:225], v[236:237]
	v_pk_fma_f32 v[86:87], v[86:87], v[218:219], v[238:239]
	v_pk_fma_f32 v[88:89], v[88:89], v[220:221], v[240:241]
	v_pk_fma_f32 v[66:67], v[66:67], v[230:231], v[242:243]
	v_pk_fma_f32 v[68:69], v[68:69], v[232:233], v[244:245]
	v_pk_fma_f32 v[70:71], v[70:71], v[226:227], v[246:247]
	v_pk_fma_f32 v[72:73], v[72:73], v[228:229], v[248:249]
	global_store_dwordx4 v155, v[86:89], s[34:35]
	global_store_dwordx4 v155, v[82:85], s[34:35] offset:16
	global_store_dwordx4 v155, v[70:73], s[34:35] offset:512
	global_store_dwordx4 v155, v[66:69], s[34:35] offset:528
	v_add_u32_e32 v157, s54, v179
	v_lshl_add_u32 v155, v157, 12, v158
	ds_read_b32 v192, v189
	global_load_dwordx4 v[234:237], v155, s[34:35] offset:16
	global_load_dwordx4 v[238:241], v155, s[34:35]
	global_load_dwordx4 v[242:245], v155, s[34:35] offset:528
	global_load_dwordx4 v[246:249], v155, s[34:35] offset:512
	s_waitcnt lgkmcnt(2)
	v_pk_mul_f32 v[46:47], v[46:47], v[196:197] op_sel_hi:[1,0]
	v_pk_mul_f32 v[48:49], v[48:49], v[196:197] op_sel_hi:[1,0]
	v_pk_mul_f32 v[42:43], v[42:43], v[196:197] op_sel_hi:[1,0]
	v_pk_mul_f32 v[44:45], v[44:45], v[196:197] op_sel_hi:[1,0]
	v_pk_mul_f32 v[38:39], v[38:39], v[196:197] op_sel_hi:[1,0]
	v_pk_mul_f32 v[40:41], v[40:41], v[196:197] op_sel_hi:[1,0]
	v_pk_mul_f32 v[34:35], v[34:35], v[196:197] op_sel_hi:[1,0]
	v_pk_mul_f32 v[36:37], v[36:37], v[196:197] op_sel_hi:[1,0]
	s_waitcnt vmcnt(16)
	v_pk_fma_f32 v[42:43], v[42:43], v[222:223], v[146:147]
	v_pk_fma_f32 v[44:45], v[44:45], v[224:225], v[148:149]
	v_pk_fma_f32 v[46:47], v[46:47], v[218:219], v[150:151]
	v_pk_fma_f32 v[48:49], v[48:49], v[220:221], v[152:153]
	v_pk_fma_f32 v[34:35], v[34:35], v[230:231], v[162:163]
	v_pk_fma_f32 v[36:37], v[36:37], v[232:233], v[164:165]
	v_pk_fma_f32 v[38:39], v[38:39], v[226:227], v[166:167]
	v_pk_fma_f32 v[40:41], v[40:41], v[228:229], v[168:169]
	global_store_dwordx4 v156, v[46:49], s[34:35]
	global_store_dwordx4 v156, v[42:45], s[34:35] offset:16
	global_store_dwordx4 v156, v[38:41], s[34:35] offset:512
	global_store_dwordx4 v156, v[34:37], s[34:35] offset:528
	s_waitcnt lgkmcnt(1)
	v_pk_mul_f32 v[30:31], v[30:31], v[250:251] op_sel_hi:[1,0]
	v_pk_mul_f32 v[32:33], v[32:33], v[250:251] op_sel_hi:[1,0]
	v_pk_mul_f32 v[26:27], v[26:27], v[250:251] op_sel_hi:[1,0]
	v_pk_mul_f32 v[28:29], v[28:29], v[250:251] op_sel_hi:[1,0]
	v_pk_mul_f32 v[22:23], v[22:23], v[250:251] op_sel_hi:[1,0]
	v_pk_mul_f32 v[24:25], v[24:25], v[250:251] op_sel_hi:[1,0]
	v_pk_mul_f32 v[18:19], v[18:19], v[250:251] op_sel_hi:[1,0]
	v_pk_mul_f32 v[20:21], v[20:21], v[250:251] op_sel_hi:[1,0]
	s_waitcnt vmcnt(12)
; __device__ __forceinline__ float swap_add(float v) { auto rr = __builtin_amdgcn_permlane32_swap(__float_as_uint(v), __float_as_uint(v), false, false); return __uint_as_float(rr[0]) + __uint_as_float(rr[1]); }
;     __device__ __forceinline__ void exchange(const f32x4 (&acc)[2][2][4][2], const Unit& u, int e, int wr, int wc, int fr, int fq) const {
;     ...
; #pragma unroll
;         for (int ai = 0; ai < 2; ++ai)
; #pragma unroll
;             for (int m = 0; m < 4; ++m) { float q = 0.f;
; #pragma unroll
;                 for (int bj = 0; bj < 2; ++bj)
; #pragma unroll
;                     for (int n = 0; n < 2; ++n) { const f32x4 v = acc[ai][bj][m][n]; q += (v[0] * v[0] + v[1] * v[1]) + (v[2] * v[2] + v[3] * v[3]); }
;                 q += __int_as_float(__builtin_amdgcn_ds_bpermute((lid ^ 16) << 2, __float_as_int(q))); q = swap_add(q);
;                 if (fq == 0) P[(ai * 128 + wr * 64 + m * 16 + fr) * 4 + wc] = q; }
;     __device__ __forceinline__ void operator()(f32x4 (&acc)[2][2][4][2], const Unit& u, int wr, int wc, int fr, int fq) const {
;     ...
; #pragma unroll
;         for (int ai = 0; ai < 2; ++ai)
; #pragma unroll
;             for (int m = 0; m < 4; ++m) { const int rl = ai * 128 + wr * 64 + m * 16 + fr; const float r1 = S[rl]; const size_t off = (size_t)(u.pm * 256 + rl) * DM + col0;
; #pragma unroll
;                 for (int bj = 0; bj < 2; ++bj) { const f32x4 xa = *(const f32x4*)(xin + off + bj * 128), xb = *(const f32x4*)(xin + off + bj * 128 + 4);
;                     const f32x4 ga = *(const f32x4*)(gpost + col0 + bj * 128), gb = *(const f32x4*)(gpost + col0 + bj * 128 + 4);
;                     const f32x4 v0 = xa + acc[ai][bj][m][0] * r1 * ga, v1 = xb + acc[ai][bj][m][1] * r1 * gb;
;                     *(f32x4*)(xout + off + bj * 128) = v0; *(f32x4*)(xout + off + bj * 128 + 4) = v1; acc[ai][bj][m][0] = v0; acc[ai][bj][m][1] = v1; }
;                 asm volatile("" ::: "memory"); }
	v_pk_fma_f32 v[26:27], v[26:27], v[222:223], v[202:203]
	v_pk_fma_f32 v[28:29], v[28:29], v[224:225], v[204:205]
	v_pk_fma_f32 v[30:31], v[30:31], v[218:219], v[206:207]
	v_pk_fma_f32 v[32:33], v[32:33], v[220:221], v[208:209]
	v_pk_fma_f32 v[18:19], v[18:19], v[230:231], v[210:211]
	v_pk_fma_f32 v[20:21], v[20:21], v[232:233], v[212:213]
	v_pk_fma_f32 v[22:23], v[22:23], v[226:227], v[214:215]
	v_pk_fma_f32 v[24:25], v[24:25], v[228:229], v[216:217]
	global_store_dwordx4 v154, v[30:33], s[34:35]
	global_store_dwordx4 v154, v[26:29], s[34:35] offset:16
	global_store_dwordx4 v154, v[22:25], s[34:35] offset:512
	global_store_dwordx4 v154, v[18:21], s[34:35] offset:528
	s_waitcnt lgkmcnt(0)
	v_pk_mul_f32 v[14:15], v[14:15], v[192:193] op_sel_hi:[1,0]
	v_pk_mul_f32 v[16:17], v[16:17], v[192:193] op_sel_hi:[1,0]
	v_pk_mul_f32 v[10:11], v[10:11], v[192:193] op_sel_hi:[1,0]
	v_pk_mul_f32 v[12:13], v[12:13], v[192:193] op_sel_hi:[1,0]
	v_pk_mul_f32 v[6:7], v[6:7], v[192:193] op_sel_hi:[1,0]
	v_pk_mul_f32 v[8:9], v[8:9], v[192:193] op_sel_hi:[1,0]
	v_pk_mul_f32 v[2:3], v[2:3], v[192:193] op_sel_hi:[1,0]
	v_pk_mul_f32 v[4:5], v[4:5], v[192:193] op_sel_hi:[1,0]
	s_waitcnt vmcnt(8)
	v_pk_fma_f32 v[10:11], v[10:11], v[222:223], v[234:235]
	v_pk_fma_f32 v[12:13], v[12:13], v[224:225], v[236:237]
	v_pk_fma_f32 v[14:15], v[14:15], v[218:219], v[238:239]
	v_pk_fma_f32 v[16:17], v[16:17], v[220:221], v[240:241]
	v_pk_fma_f32 v[2:3], v[2:3], v[230:231], v[242:243]
	v_pk_fma_f32 v[4:5], v[4:5], v[232:233], v[244:245]
	v_pk_fma_f32 v[6:7], v[6:7], v[226:227], v[246:247]
	v_pk_fma_f32 v[8:9], v[8:9], v[228:229], v[248:249]
	global_store_dwordx4 v155, v[14:17], s[34:35]
	global_store_dwordx4 v155, v[10:13], s[34:35] offset:16
	global_store_dwordx4 v155, v[6:9], s[34:35] offset:512
	global_store_dwordx4 v155, v[2:5], s[34:35] offset:528
	v_add_u32_e32 v146, s54, v173
	v_ashrrev_i32_e32 v147, 31, v146
	v_add_u32_e32 v148, s54, v174
	v_ashrrev_i32_e32 v149, 31, v148
	v_add_u32_e32 v150, s54, v175
	v_ashrrev_i32_e32 v151, 31, v150
	v_add_u32_e32 v152, s54, v176
	v_ashrrev_i32_e32 v153, 31, v152
	v_add_u32_e32 v156, s54, v177
	v_ashrrev_i32_e32 v157, 31, v156
	v_add_u32_e32 v166, s54, v178
	v_ashrrev_i32_e32 v167, 31, v166
	v_add_u32_e32 v168, s54, v179
	v_ashrrev_i32_e32 v169, 31, v168
	s_cbranch_vccnz .LBB0_140
	v_mul_f32_e32 v154, v51, v51
	v_mul_f32_e32 v155, v53, v53
	v_fmac_f32_e32 v154, v50, v50
	v_fmac_f32_e32 v155, v52, v52
	v_add_f32_e32 v154, v154, v155
	v_mul_f32_e32 v155, v55, v55
	v_mul_f32_e32 v158, v57, v57
	v_fmac_f32_e32 v155, v54, v54
	v_fmac_f32_e32 v158, v56, v56
	v_add_f32_e32 v155, v155, v158
	v_add_f32_e32 v154, v154, v155
	v_mul_f32_e32 v155, v63, v63
	v_mul_f32_e32 v158, v65, v65
	v_fmac_f32_e32 v155, v62, v62
	v_fmac_f32_e32 v158, v64, v64
	v_add_f32_e32 v155, v155, v158
	v_add_f32_e32 v154, v154, v155
	v_mul_f32_e32 v155, v59, v59
	v_mul_f32_e32 v158, v61, v61
	v_fmac_f32_e32 v155, v58, v58
	v_fmac_f32_e32 v158, v60, v60
	v_add_f32_e32 v155, v155, v158
	v_add_f32_e32 v154, v154, v155
	ds_bpermute_b32 v155, v172, v154
	s_waitcnt lgkmcnt(0)
	v_add_f32_e32 v154, v154, v155
	v_mov_b32_e32 v155, v154
	s_nop 1
	v_permlane32_swap_b32_e32 v154, v155
	s_and_saveexec_b64 s[54:55], s[42:43]
	v_add_f32_e32 v154, v154, v155
	ds_write_b32 v201, v154
	s_or_b64 exec, exec, s[54:55]
	v_mul_f32_e32 v154, v75, v75
	v_mul_f32_e32 v155, v77, v77
	v_fmac_f32_e32 v154, v74, v74
	v_fmac_f32_e32 v155, v76, v76
	v_add_f32_e32 v154, v154, v155
	v_mul_f32_e32 v155, v79, v79
	v_mul_f32_e32 v158, v81, v81
	v_fmac_f32_e32 v155, v78, v78
	v_fmac_f32_e32 v158, v80, v80
	v_add_f32_e32 v155, v155, v158
	v_add_f32_e32 v154, v154, v155
	v_mul_f32_e32 v155, v95, v95
	v_mul_f32_e32 v158, v97, v97
	v_fmac_f32_e32 v155, v94, v94
	v_fmac_f32_e32 v158, v96, v96
	v_add_f32_e32 v155, v155, v158
	v_add_f32_e32 v154, v154, v155
	v_mul_f32_e32 v155, v91, v91
	v_mul_f32_e32 v158, v93, v93
	v_fmac_f32_e32 v155, v90, v90
	v_fmac_f32_e32 v158, v92, v92
	v_add_f32_e32 v155, v155, v158
	v_add_f32_e32 v154, v154, v155
	ds_bpermute_b32 v155, v172, v154
	s_waitcnt lgkmcnt(0)
	v_add_f32_e32 v154, v154, v155
	v_mov_b32_e32 v155, v154
	s_nop 1
	v_permlane32_swap_b32_e32 v154, v155
	s_and_saveexec_b64 s[54:55], s[42:43]
	v_add_f32_e32 v154, v154, v155
	ds_write_b32 v201, v154 offset:256
	s_or_b64 exec, exec, s[54:55]
	v_mul_f32_e32 v154, v99, v99
	v_mul_f32_e32 v155, v101, v101
	v_fmac_f32_e32 v154, v98, v98
	v_fmac_f32_e32 v155, v100, v100
	v_add_f32_e32 v154, v154, v155
	v_mul_f32_e32 v155, v103, v103
	v_mul_f32_e32 v158, v105, v105
	v_fmac_f32_e32 v155, v102, v102
	v_fmac_f32_e32 v158, v104, v104
	v_add_f32_e32 v155, v155, v158
	v_add_f32_e32 v154, v154, v155
	v_mul_f32_e32 v155, v119, v119
	v_mul_f32_e32 v158, v121, v121
	v_fmac_f32_e32 v155, v118, v118
	v_fmac_f32_e32 v158, v120, v120
	v_add_f32_e32 v155, v155, v158
	v_add_f32_e32 v154, v154, v155
	v_mul_f32_e32 v155, v115, v115
	v_mul_f32_e32 v158, v117, v117
	v_fmac_f32_e32 v155, v114, v114
	v_fmac_f32_e32 v158, v116, v116
	v_add_f32_e32 v155, v155, v158
	v_add_f32_e32 v154, v154, v155
	ds_bpermute_b32 v155, v172, v154
	s_waitcnt lgkmcnt(0)
; __device__ __forceinline__ float swap_add(float v) { auto rr = __builtin_amdgcn_permlane32_swap(__float_as_uint(v), __float_as_uint(v), false, false); return __uint_as_float(rr[0]) + __uint_as_float(rr[1]); }
;     __device__ __forceinline__ void exchange(const f32x4 (&acc)[2][2][4][2], const Unit& u, int e, int wr, int wc, int fr, int fq) const {
;     ...
; #pragma unroll
;         for (int ai = 0; ai < 2; ++ai)
; #pragma unroll
;             for (int m = 0; m < 4; ++m) { float q = 0.f;
; #pragma unroll
;                 for (int bj = 0; bj < 2; ++bj)
; #pragma unroll
;                     for (int n = 0; n < 2; ++n) { const f32x4 v = acc[ai][bj][m][n]; q += (v[0] * v[0] + v[1] * v[1]) + (v[2] * v[2] + v[3] * v[3]); }
;                 q += __int_as_float(__builtin_amdgcn_ds_bpermute((lid ^ 16) << 2, __float_as_int(q))); q = swap_add(q);
;                 if (fq == 0) P[(ai * 128 + wr * 64 + m * 16 + fr) * 4 + wc] = q; }
;         __syncthreads();
;         float* xb = xbuf + (size_t)e * T * 4 + (size_t)u.pm * 256 * 4; unsigned* c = cnt + (e * 64 + u.pm) * 64;
;         if (tid < 256) { const float tot = (P[tid * 4] + P[tid * 4 + 1]) + (P[tid * 4 + 2] + P[tid * 4 + 3]);
;             __hip_atomic_store(xb + tid * 4 + u.pn, tot, __ATOMIC_RELAXED, __HIP_MEMORY_SCOPE_AGENT); }
	v_add_f32_e32 v154, v154, v155
	v_mov_b32_e32 v155, v154
	s_nop 1
	v_permlane32_swap_b32_e32 v154, v155
	s_and_saveexec_b64 s[54:55], s[42:43]
	v_add_f32_e32 v154, v154, v155
	ds_write_b32 v201, v154 offset:512
	s_or_b64 exec, exec, s[54:55]
	v_mul_f32_e32 v154, v127, v127
	v_mul_f32_e32 v155, v129, v129
	v_fmac_f32_e32 v154, v126, v126
	v_fmac_f32_e32 v155, v128, v128
	v_add_f32_e32 v154, v154, v155
	v_mul_f32_e32 v155, v123, v123
	v_mul_f32_e32 v158, v125, v125
	v_fmac_f32_e32 v155, v122, v122
	v_fmac_f32_e32 v158, v124, v124
	v_add_f32_e32 v155, v155, v158
	v_add_f32_e32 v154, v154, v155
	v_mul_f32_e32 v155, v111, v111
	v_mul_f32_e32 v158, v113, v113
	v_fmac_f32_e32 v155, v110, v110
	v_fmac_f32_e32 v158, v112, v112
	v_add_f32_e32 v155, v155, v158
	v_add_f32_e32 v154, v154, v155
	v_mul_f32_e32 v155, v107, v107
	v_mul_f32_e32 v158, v109, v109
	v_fmac_f32_e32 v155, v106, v106
	v_fmac_f32_e32 v158, v108, v108
	v_add_f32_e32 v155, v155, v158
	v_add_f32_e32 v154, v154, v155
	ds_bpermute_b32 v155, v172, v154
	s_waitcnt lgkmcnt(0)
	v_add_f32_e32 v154, v154, v155
	v_mov_b32_e32 v155, v154
	s_nop 1
	v_permlane32_swap_b32_e32 v154, v155
	s_and_saveexec_b64 s[54:55], s[42:43]
	v_add_f32_e32 v154, v154, v155
	ds_write_b32 v201, v154 offset:768
	s_or_b64 exec, exec, s[54:55]
	v_mul_f32_e32 v154, v87, v87
	v_mul_f32_e32 v155, v89, v89
	v_fmac_f32_e32 v154, v86, v86
	v_fmac_f32_e32 v155, v88, v88
	v_add_f32_e32 v154, v154, v155
	v_mul_f32_e32 v155, v83, v83
	v_mul_f32_e32 v158, v85, v85
	v_fmac_f32_e32 v155, v82, v82
	v_fmac_f32_e32 v158, v84, v84
	v_add_f32_e32 v155, v155, v158
	v_add_f32_e32 v154, v154, v155
	v_mul_f32_e32 v155, v71, v71
	v_mul_f32_e32 v158, v73, v73
	v_fmac_f32_e32 v155, v70, v70
	v_fmac_f32_e32 v158, v72, v72
	v_add_f32_e32 v155, v155, v158
	v_add_f32_e32 v154, v154, v155
	v_mul_f32_e32 v155, v67, v67
	v_mul_f32_e32 v158, v69, v69
	v_fmac_f32_e32 v155, v66, v66
	v_fmac_f32_e32 v158, v68, v68
	v_add_f32_e32 v155, v155, v158
	v_add_f32_e32 v154, v154, v155
	ds_bpermute_b32 v155, v172, v154
	s_waitcnt lgkmcnt(0)
	v_add_f32_e32 v154, v154, v155
	v_mov_b32_e32 v155, v154
	s_nop 1
	v_permlane32_swap_b32_e32 v154, v155
	s_and_saveexec_b64 s[54:55], s[42:43]
	v_add_f32_e32 v154, v154, v155
	ds_write_b32 v201, v154 offset:2048
	s_or_b64 exec, exec, s[54:55]
	v_mul_f32_e32 v154, v47, v47
	v_mul_f32_e32 v155, v49, v49
	v_fmac_f32_e32 v154, v46, v46
	v_fmac_f32_e32 v155, v48, v48
	v_add_f32_e32 v154, v154, v155
	v_mul_f32_e32 v155, v43, v43
	v_mul_f32_e32 v158, v45, v45
	v_fmac_f32_e32 v155, v42, v42
	v_fmac_f32_e32 v158, v44, v44
	v_add_f32_e32 v155, v155, v158
	v_add_f32_e32 v154, v154, v155
	v_mul_f32_e32 v155, v39, v39
	v_mul_f32_e32 v158, v41, v41
	v_fmac_f32_e32 v155, v38, v38
	v_fmac_f32_e32 v158, v40, v40
	v_add_f32_e32 v155, v155, v158
	v_add_f32_e32 v154, v154, v155
	v_mul_f32_e32 v155, v35, v35
	v_mul_f32_e32 v158, v37, v37
	v_fmac_f32_e32 v155, v34, v34
	v_fmac_f32_e32 v158, v36, v36
	v_add_f32_e32 v155, v155, v158
	v_add_f32_e32 v154, v154, v155
	ds_bpermute_b32 v155, v172, v154
	s_waitcnt lgkmcnt(0)
	v_add_f32_e32 v154, v154, v155
	v_mov_b32_e32 v155, v154
	s_nop 1
	v_permlane32_swap_b32_e32 v154, v155
	s_and_saveexec_b64 s[54:55], s[42:43]
	v_add_f32_e32 v154, v154, v155
	ds_write_b32 v201, v154 offset:2304
	s_or_b64 exec, exec, s[54:55]
	v_mul_f32_e32 v154, v31, v31
	v_mul_f32_e32 v155, v33, v33
	v_fmac_f32_e32 v154, v30, v30
	v_fmac_f32_e32 v155, v32, v32
	v_add_f32_e32 v154, v154, v155
	v_mul_f32_e32 v155, v27, v27
	v_mul_f32_e32 v158, v29, v29
	v_fmac_f32_e32 v155, v26, v26
	v_fmac_f32_e32 v158, v28, v28
	v_add_f32_e32 v155, v155, v158
	v_add_f32_e32 v154, v154, v155
	v_mul_f32_e32 v155, v23, v23
	v_mul_f32_e32 v158, v25, v25
	v_fmac_f32_e32 v155, v22, v22
	v_fmac_f32_e32 v158, v24, v24
	v_add_f32_e32 v155, v155, v158
	v_add_f32_e32 v154, v154, v155
	v_mul_f32_e32 v155, v19, v19
	v_mul_f32_e32 v158, v21, v21
	v_fmac_f32_e32 v155, v18, v18
	v_fmac_f32_e32 v158, v20, v20
	v_add_f32_e32 v155, v155, v158
	v_add_f32_e32 v154, v154, v155
	ds_bpermute_b32 v155, v172, v154
	s_waitcnt lgkmcnt(0)
	v_add_f32_e32 v154, v154, v155
	v_mov_b32_e32 v155, v154
	s_nop 1
	v_permlane32_swap_b32_e32 v154, v155
	s_and_saveexec_b64 s[54:55], s[42:43]
	v_add_f32_e32 v154, v154, v155
	ds_write_b32 v201, v154 offset:2560
	s_or_b64 exec, exec, s[54:55]
	v_mul_f32_e32 v154, v15, v15
	v_mul_f32_e32 v155, v17, v17
	v_fmac_f32_e32 v154, v14, v14
	v_fmac_f32_e32 v155, v16, v16
	v_add_f32_e32 v154, v154, v155
	v_mul_f32_e32 v155, v11, v11
	v_mul_f32_e32 v158, v13, v13
	v_fmac_f32_e32 v155, v10, v10
	v_fmac_f32_e32 v158, v12, v12
	v_add_f32_e32 v155, v155, v158
	v_add_f32_e32 v154, v154, v155
	v_mul_f32_e32 v155, v7, v7
	v_mul_f32_e32 v158, v9, v9
	v_fmac_f32_e32 v155, v6, v6
	v_fmac_f32_e32 v158, v8, v8
	v_add_f32_e32 v155, v155, v158
	v_add_f32_e32 v154, v154, v155
	v_mul_f32_e32 v155, v3, v3
	v_mul_f32_e32 v158, v5, v5
	v_fmac_f32_e32 v155, v2, v2
	v_fmac_f32_e32 v158, v4, v4
	v_add_f32_e32 v155, v155, v158
	v_add_f32_e32 v154, v154, v155
	ds_bpermute_b32 v155, v172, v154
	s_waitcnt lgkmcnt(0)
	v_add_f32_e32 v154, v154, v155
	v_mov_b32_e32 v155, v154
	s_nop 1
	v_permlane32_swap_b32_e32 v154, v155
	s_and_saveexec_b64 s[54:55], s[42:43]
	v_add_f32_e32 v154, v154, v155
	ds_write_b32 v201, v154 offset:2816
	s_or_b64 exec, exec, s[54:55]
	s_add_u32 s12, s92, s12
	s_addc_u32 s13, s94, s13
	v_lshl_add_u64 v[154:155], v[136:137], 2, s[12:13]
	s_waitcnt lgkmcnt(0)
	s_barrier
	s_and_saveexec_b64 s[12:13], s[44:45]
	s_cbranch_execz .LBB0_122
	ds_read_b128 v[202:205], v180
	s_ashr_i32 s79, s78, 31
	v_lshl_add_u64 v[160:161], s[78:79], 2, v[154:155]
	s_waitcnt lgkmcnt(0)
	v_mov_b32_e32 v158, v203
	v_mov_b32_e32 v159, v204
	v_mov_b32_e32 v203, v205
	v_pk_add_f32 v[158:159], v[158:159], v[202:203]
	s_nop 0
	v_pk_add_f32 v[158:159], v[158:159], v[158:159] op_sel:[0,1] op_sel_hi:[1,0]
	global_store_dword v[160:161], v158, off sc1

; #define LAS __attribute__((address_space(3)))
;     __device__ __forceinline__ void operator()(f32x4 (&acc)[2][2][4][2], const Unit& u, int wr, int wc, int fr, int fq) const {
;         const LAS float* S = (const LAS float*)(lds + EN_S);
;         const int col0 = u.pn * 256 + wc * 32 + 8 * fq;
;         exchange(acc, u, 0, wr, wc, fr, fq);
; #pragma unroll
;         for (int ai = 0; ai < 2; ++ai)
; #pragma unroll
;             for (int m = 0; m < 4; ++m) { const int rl = ai * 128 + wr * 64 + m * 16 + fr; const float r1 = S[rl]; const size_t off = (size_t)(u.pm * 256 + rl) * DM + col0;
; #pragma unroll
;                 for (int bj = 0; bj < 2; ++bj) { const f32x4 xa = *(const f32x4*)(xin + off + bj * 128), xb = *(const f32x4*)(xin + off + bj * 128 + 4);
;                     const f32x4 ga = *(const f32x4*)(gpost + col0 + bj * 128), gb = *(const f32x4*)(gpost + col0 + bj * 128 + 4);
;                     const f32x4 v0 = xa + acc[ai][bj][m][0] * r1 * ga, v1 = xb + acc[ai][bj][m][1] * r1 * gb;
;                     *(f32x4*)(xout + off + bj * 128) = v0; *(f32x4*)(xout + off + bj * 128 + 4) = v1; acc[ai][bj][m][0] = v0; acc[ai][bj][m][1] = v1; }
;                 asm volatile("" ::: "memory"); }
.LBB0_235:
	s_or_b64 exec, exec, s[84:85]
	s_lshl_b32 s54, s82, 8
	v_add_u32_e32 v144, s54, v169
	v_lshl_or_b32 v142, s76, 8, v189
	v_ashrrev_i32_e32 v145, 31, v144
	v_ashrrev_i32_e32 v143, 31, v142
	v_lshlrev_b64 v[146:147], 10, v[144:145]
	v_lshl_add_u64 v[146:147], v[146:147], 0, v[142:143]
	v_lshlrev_b64 v[162:163], 2, v[146:147]
	v_lshl_add_u64 v[164:165], s[34:35], 0, v[162:163]
	v_lshl_add_u64 v[154:155], v[142:143], 2, s[52:53]
	global_load_dwordx4 v[218:221], v[154:155], off
	global_load_dwordx4 v[222:225], v[154:155], off offset:16
	global_load_dwordx4 v[226:229], v[154:155], off offset:512
	global_load_dwordx4 v[230:233], v[154:155], off offset:528
	s_waitcnt lgkmcnt(0)
	s_barrier
	s_andn2_b64 vcc, exec, s[70:71]
	v_lshl_add_u32 v165, v144, 10, v142
	v_lshlrev_b32_e32 v162, 2, v165
	ds_read_b32 v250, v181
	global_load_dwordx4 v[202:205], v162, s[34:35] offset:16
	global_load_dwordx4 v[206:209], v162, s[34:35]
	global_load_dwordx4 v[210:213], v162, s[34:35] offset:528
	global_load_dwordx4 v[214:217], v162, s[34:35] offset:512
	v_add_u32_e32 v165, s54, v172
	v_lshl_add_u32 v165, v165, 10, v142
	v_lshlrev_b32_e32 v163, 2, v165
	ds_read_b32 v192, v182
	global_load_dwordx4 v[234:237], v163, s[34:35] offset:16
	global_load_dwordx4 v[238:241], v163, s[34:35]
	global_load_dwordx4 v[242:245], v163, s[34:35] offset:528
	global_load_dwordx4 v[246:249], v163, s[34:35] offset:512
	v_add_u32_e32 v165, s54, v173
	v_lshl_add_u32 v165, v165, 10, v142
	v_lshlrev_b32_e32 v164, 2, v165
	ds_read_b32 v196, v183
	global_load_dwordx4 v[146:149], v164, s[34:35] offset:16
	global_load_dwordx4 v[150:153], v164, s[34:35]
	global_load_dwordx4 v[154:157], v164, s[34:35] offset:528
	global_load_dwordx4 v[158:161], v164, s[34:35] offset:512
	s_waitcnt lgkmcnt(2)
	v_pk_mul_f32 v[42:43], v[42:43], v[250:251] op_sel_hi:[1,0]
	v_pk_mul_f32 v[44:45], v[44:45], v[250:251] op_sel_hi:[1,0]
	v_pk_mul_f32 v[46:47], v[46:47], v[250:251] op_sel_hi:[1,0]
	v_pk_mul_f32 v[48:49], v[48:49], v[250:251] op_sel_hi:[1,0]
	v_pk_mul_f32 v[62:63], v[62:63], v[250:251] op_sel_hi:[1,0]
	v_pk_mul_f32 v[64:65], v[64:65], v[250:251] op_sel_hi:[1,0]
	v_pk_mul_f32 v[58:59], v[58:59], v[250:251] op_sel_hi:[1,0]
	v_pk_mul_f32 v[60:61], v[60:61], v[250:251] op_sel_hi:[1,0]
	s_waitcnt vmcnt(8)
	v_pk_fma_f32 v[46:47], v[46:47], v[222:223], v[202:203]
	v_pk_fma_f32 v[48:49], v[48:49], v[224:225], v[204:205]
	v_pk_fma_f32 v[42:43], v[42:43], v[218:219], v[206:207]
	v_pk_fma_f32 v[44:45], v[44:45], v[220:221], v[208:209]
	v_pk_fma_f32 v[58:59], v[58:59], v[230:231], v[210:211]
	v_pk_fma_f32 v[60:61], v[60:61], v[232:233], v[212:213]
	v_pk_fma_f32 v[62:63], v[62:63], v[226:227], v[214:215]
	v_pk_fma_f32 v[64:65], v[64:65], v[228:229], v[216:217]
	global_store_dwordx4 v162, v[42:45], s[14:15]
	global_store_dwordx4 v162, v[46:49], s[14:15] offset:16
	global_store_dwordx4 v162, v[62:65], s[14:15] offset:512
	global_store_dwordx4 v162, v[58:61], s[14:15] offset:528
	v_add_u32_e32 v165, s54, v174
	v_lshl_add_u32 v165, v165, 10, v142
	v_lshlrev_b32_e32 v162, 2, v165
	ds_read_b32 v250, v184
	global_load_dwordx4 v[202:205], v162, s[34:35] offset:16
	global_load_dwordx4 v[206:209], v162, s[34:35]
	global_load_dwordx4 v[210:213], v162, s[34:35] offset:528
	global_load_dwordx4 v[214:217], v162, s[34:35] offset:512
	s_waitcnt lgkmcnt(2)
	v_pk_mul_f32 v[66:67], v[66:67], v[192:193] op_sel_hi:[1,0]
	v_pk_mul_f32 v[68:69], v[68:69], v[192:193] op_sel_hi:[1,0]
	v_pk_mul_f32 v[70:71], v[70:71], v[192:193] op_sel_hi:[1,0]
	v_pk_mul_f32 v[72:73], v[72:73], v[192:193] op_sel_hi:[1,0]
	v_pk_mul_f32 v[86:87], v[86:87], v[192:193] op_sel_hi:[1,0]
	v_pk_mul_f32 v[88:89], v[88:89], v[192:193] op_sel_hi:[1,0]
	v_pk_mul_f32 v[82:83], v[82:83], v[192:193] op_sel_hi:[1,0]
	v_pk_mul_f32 v[84:85], v[84:85], v[192:193] op_sel_hi:[1,0]
	s_waitcnt vmcnt(12)
	v_pk_fma_f32 v[70:71], v[70:71], v[222:223], v[234:235]
	v_pk_fma_f32 v[72:73], v[72:73], v[224:225], v[236:237]
	v_pk_fma_f32 v[66:67], v[66:67], v[218:219], v[238:239]
	v_pk_fma_f32 v[68:69], v[68:69], v[220:221], v[240:241]
	v_pk_fma_f32 v[82:83], v[82:83], v[230:231], v[242:243]
	v_pk_fma_f32 v[84:85], v[84:85], v[232:233], v[244:245]
	v_pk_fma_f32 v[86:87], v[86:87], v[226:227], v[246:247]
	v_pk_fma_f32 v[88:89], v[88:89], v[228:229], v[248:249]
	global_store_dwordx4 v163, v[66:69], s[14:15]
	global_store_dwordx4 v163, v[70:73], s[14:15] offset:16
	global_store_dwordx4 v163, v[86:89], s[14:15] offset:512
	global_store_dwordx4 v163, v[82:85], s[14:15] offset:528
	v_add_u32_e32 v165, s54, v175
	v_lshl_add_u32 v165, v165, 10, v142
	v_lshlrev_b32_e32 v163, 2, v165
	ds_read_b32 v192, v185
	global_load_dwordx4 v[234:237], v163, s[34:35] offset:16
	global_load_dwordx4 v[238:241], v163, s[34:35]
	global_load_dwordx4 v[242:245], v163, s[34:35] offset:528
	global_load_dwordx4 v[246:249], v163, s[34:35] offset:512
	s_waitcnt lgkmcnt(2)
	v_pk_mul_f32 v[98:99], v[98:99], v[196:197] op_sel_hi:[1,0]
	v_pk_mul_f32 v[100:101], v[100:101], v[196:197] op_sel_hi:[1,0]
	v_pk_mul_f32 v[102:103], v[102:103], v[196:197] op_sel_hi:[1,0]
	v_pk_mul_f32 v[104:105], v[104:105], v[196:197] op_sel_hi:[1,0]
	v_pk_mul_f32 v[110:111], v[110:111], v[196:197] op_sel_hi:[1,0]
	v_pk_mul_f32 v[112:113], v[112:113], v[196:197] op_sel_hi:[1,0]
	v_pk_mul_f32 v[106:107], v[106:107], v[196:197] op_sel_hi:[1,0]
	v_pk_mul_f32 v[108:109], v[108:109], v[196:197] op_sel_hi:[1,0]
	s_waitcnt vmcnt(16)
;     __device__ __forceinline__ void operator()(f32x4 (&acc)[2][2][4][2], const Unit& u, int wr, int wc, int fr, int fq) const {
;     ...
; #pragma unroll
;         for (int ai = 0; ai < 2; ++ai)
; #pragma unroll
;             for (int m = 0; m < 4; ++m) { const int rl = ai * 128 + wr * 64 + m * 16 + fr; const float r1 = S[rl]; const size_t off = (size_t)(u.pm * 256 + rl) * DM + col0;
; #pragma unroll
;                 for (int bj = 0; bj < 2; ++bj) { const f32x4 xa = *(const f32x4*)(xin + off + bj * 128), xb = *(const f32x4*)(xin + off + bj * 128 + 4);
;                     const f32x4 ga = *(const f32x4*)(gpost + col0 + bj * 128), gb = *(const f32x4*)(gpost + col0 + bj * 128 + 4);
;                     const f32x4 v0 = xa + acc[ai][bj][m][0] * r1 * ga, v1 = xb + acc[ai][bj][m][1] * r1 * gb;
;                     *(f32x4*)(xout + off + bj * 128) = v0; *(f32x4*)(xout + off + bj * 128 + 4) = v1; acc[ai][bj][m][0] = v0; acc[ai][bj][m][1] = v1; }
;                 asm volatile("" ::: "memory"); }
	v_pk_fma_f32 v[102:103], v[102:103], v[222:223], v[146:147]
	v_pk_fma_f32 v[104:105], v[104:105], v[224:225], v[148:149]
	v_pk_fma_f32 v[98:99], v[98:99], v[218:219], v[150:151]
	v_pk_fma_f32 v[100:101], v[100:101], v[220:221], v[152:153]
	v_pk_fma_f32 v[106:107], v[106:107], v[230:231], v[154:155]
	v_pk_fma_f32 v[108:109], v[108:109], v[232:233], v[156:157]
	v_pk_fma_f32 v[110:111], v[110:111], v[226:227], v[158:159]
	v_pk_fma_f32 v[112:113], v[112:113], v[228:229], v[160:161]
	global_store_dwordx4 v164, v[98:101], s[14:15]
	global_store_dwordx4 v164, v[102:105], s[14:15] offset:16
	global_store_dwordx4 v164, v[110:113], s[14:15] offset:512
	global_store_dwordx4 v164, v[106:109], s[14:15] offset:528
	v_add_u32_e32 v165, s54, v176
	v_lshl_add_u32 v165, v165, 10, v142
	v_lshlrev_b32_e32 v164, 2, v165
	ds_read_b32 v196, v186
	global_load_dwordx4 v[146:149], v164, s[34:35] offset:16
	global_load_dwordx4 v[150:153], v164, s[34:35]
	global_load_dwordx4 v[154:157], v164, s[34:35] offset:528
	global_load_dwordx4 v[158:161], v164, s[34:35] offset:512
	s_waitcnt lgkmcnt(2)
	v_pk_mul_f32 v[122:123], v[122:123], v[250:251] op_sel_hi:[1,0]
	v_pk_mul_f32 v[124:125], v[124:125], v[250:251] op_sel_hi:[1,0]
	v_pk_mul_f32 v[126:127], v[126:127], v[250:251] op_sel_hi:[1,0]
	v_pk_mul_f32 v[128:129], v[128:129], v[250:251] op_sel_hi:[1,0]
	v_pk_mul_f32 v[118:119], v[118:119], v[250:251] op_sel_hi:[1,0]
	v_pk_mul_f32 v[120:121], v[120:121], v[250:251] op_sel_hi:[1,0]
	v_pk_mul_f32 v[114:115], v[114:115], v[250:251] op_sel_hi:[1,0]
	v_pk_mul_f32 v[116:117], v[116:117], v[250:251] op_sel_hi:[1,0]
	s_waitcnt vmcnt(16)
	v_pk_fma_f32 v[126:127], v[126:127], v[222:223], v[202:203]
	v_pk_fma_f32 v[128:129], v[128:129], v[224:225], v[204:205]
	v_pk_fma_f32 v[122:123], v[122:123], v[218:219], v[206:207]
	v_pk_fma_f32 v[124:125], v[124:125], v[220:221], v[208:209]
	v_pk_fma_f32 v[114:115], v[114:115], v[230:231], v[210:211]
	v_pk_fma_f32 v[116:117], v[116:117], v[232:233], v[212:213]
	v_pk_fma_f32 v[118:119], v[118:119], v[226:227], v[214:215]
	v_pk_fma_f32 v[120:121], v[120:121], v[228:229], v[216:217]
	global_store_dwordx4 v162, v[122:125], s[14:15]
	global_store_dwordx4 v162, v[126:129], s[14:15] offset:16
	global_store_dwordx4 v162, v[118:121], s[14:15] offset:512
	global_store_dwordx4 v162, v[114:117], s[14:15] offset:528
	v_add_u32_e32 v165, s54, v177
	v_lshl_add_u32 v165, v165, 10, v142
	v_lshlrev_b32_e32 v162, 2, v165
	ds_read_b32 v250, v187
	global_load_dwordx4 v[202:205], v162, s[34:35] offset:16
	global_load_dwordx4 v[206:209], v162, s[34:35]
	global_load_dwordx4 v[210:213], v162, s[34:35] offset:528
	global_load_dwordx4 v[214:217], v162, s[34:35] offset:512
	s_waitcnt lgkmcnt(2)
	v_pk_mul_f32 v[94:95], v[94:95], v[192:193] op_sel_hi:[1,0]
	v_pk_mul_f32 v[96:97], v[96:97], v[192:193] op_sel_hi:[1,0]
	v_pk_mul_f32 v[90:91], v[90:91], v[192:193] op_sel_hi:[1,0]
	v_pk_mul_f32 v[92:93], v[92:93], v[192:193] op_sel_hi:[1,0]
	v_pk_mul_f32 v[78:79], v[78:79], v[192:193] op_sel_hi:[1,0]
	v_pk_mul_f32 v[80:81], v[80:81], v[192:193] op_sel_hi:[1,0]
	v_pk_mul_f32 v[74:75], v[74:75], v[192:193] op_sel_hi:[1,0]
	v_pk_mul_f32 v[76:77], v[76:77], v[192:193] op_sel_hi:[1,0]
	s_waitcnt vmcnt(16)
	v_pk_fma_f32 v[90:91], v[90:91], v[222:223], v[234:235]
	v_pk_fma_f32 v[92:93], v[92:93], v[224:225], v[236:237]
	v_pk_fma_f32 v[94:95], v[94:95], v[218:219], v[238:239]
	v_pk_fma_f32 v[96:97], v[96:97], v[220:221], v[240:241]
	v_pk_fma_f32 v[74:75], v[74:75], v[230:231], v[242:243]
	v_pk_fma_f32 v[76:77], v[76:77], v[232:233], v[244:245]
	v_pk_fma_f32 v[78:79], v[78:79], v[226:227], v[246:247]
	v_pk_fma_f32 v[80:81], v[80:81], v[228:229], v[248:249]
	global_store_dwordx4 v163, v[94:97], s[14:15]
	global_store_dwordx4 v163, v[90:93], s[14:15] offset:16
	global_store_dwordx4 v163, v[78:81], s[14:15] offset:512
	global_store_dwordx4 v163, v[74:77], s[14:15] offset:528
	v_add_u32_e32 v165, s54, v178
	v_lshl_add_u32 v165, v165, 10, v142
	v_lshlrev_b32_e32 v163, 2, v165
	ds_read_b32 v192, v188
	global_load_dwordx4 v[234:237], v163, s[34:35] offset:16
	global_load_dwordx4 v[238:241], v163, s[34:35]
	global_load_dwordx4 v[242:245], v163, s[34:35] offset:528
	global_load_dwordx4 v[246:249], v163, s[34:35] offset:512
	s_waitcnt lgkmcnt(2)
	v_pk_mul_f32 v[54:55], v[54:55], v[196:197] op_sel_hi:[1,0]
	v_pk_mul_f32 v[56:57], v[56:57], v[196:197] op_sel_hi:[1,0]
	v_pk_mul_f32 v[50:51], v[50:51], v[196:197] op_sel_hi:[1,0]
	v_pk_mul_f32 v[52:53], v[52:53], v[196:197] op_sel_hi:[1,0]
	v_pk_mul_f32 v[38:39], v[38:39], v[196:197] op_sel_hi:[1,0]
	v_pk_mul_f32 v[40:41], v[40:41], v[196:197] op_sel_hi:[1,0]
	v_pk_mul_f32 v[34:35], v[34:35], v[196:197] op_sel_hi:[1,0]
	v_pk_mul_f32 v[36:37], v[36:37], v[196:197] op_sel_hi:[1,0]
	s_waitcnt vmcnt(16)
	v_pk_fma_f32 v[50:51], v[50:51], v[222:223], v[146:147]
	v_pk_fma_f32 v[52:53], v[52:53], v[224:225], v[148:149]
	v_pk_fma_f32 v[54:55], v[54:55], v[218:219], v[150:151]
	v_pk_fma_f32 v[56:57], v[56:57], v[220:221], v[152:153]
	v_pk_fma_f32 v[34:35], v[34:35], v[230:231], v[154:155]
	v_pk_fma_f32 v[36:37], v[36:37], v[232:233], v[156:157]
	v_pk_fma_f32 v[38:39], v[38:39], v[226:227], v[158:159]
	v_pk_fma_f32 v[40:41], v[40:41], v[228:229], v[160:161]
	global_store_dwordx4 v164, v[54:57], s[14:15]
	global_store_dwordx4 v164, v[50:53], s[14:15] offset:16
	global_store_dwordx4 v164, v[38:41], s[14:15] offset:512
	global_store_dwordx4 v164, v[34:37], s[14:15] offset:528
	s_waitcnt lgkmcnt(1)
; __device__ __forceinline__ float swap_add(float v) { auto rr = __builtin_amdgcn_permlane32_swap(__float_as_uint(v), __float_as_uint(v), false, false); return __uint_as_float(rr[0]) + __uint_as_float(rr[1]); }
;     __device__ __forceinline__ void exchange(const f32x4 (&acc)[2][2][4][2], const Unit& u, int e, int wr, int wc, int fr, int fq) const {
;     ...
; #pragma unroll
;         for (int ai = 0; ai < 2; ++ai)
; #pragma unroll
;             for (int m = 0; m < 4; ++m) { float q = 0.f;
; #pragma unroll
;                 for (int bj = 0; bj < 2; ++bj)
; #pragma unroll
;                     for (int n = 0; n < 2; ++n) { const f32x4 v = acc[ai][bj][m][n]; q += (v[0] * v[0] + v[1] * v[1]) + (v[2] * v[2] + v[3] * v[3]); }
;                 q += __int_as_float(__builtin_amdgcn_ds_bpermute((lid ^ 16) << 2, __float_as_int(q))); q = swap_add(q);
;                 if (fq == 0) P[(ai * 128 + wr * 64 + m * 16 + fr) * 4 + wc] = q; }
;     __device__ __forceinline__ void operator()(f32x4 (&acc)[2][2][4][2], const Unit& u, int wr, int wc, int fr, int fq) const {
;     ...
; #pragma unroll
;         for (int ai = 0; ai < 2; ++ai)
; #pragma unroll
;             for (int m = 0; m < 4; ++m) { const int rl = ai * 128 + wr * 64 + m * 16 + fr; const float r1 = S[rl]; const size_t off = (size_t)(u.pm * 256 + rl) * DM + col0;
; #pragma unroll
;                 for (int bj = 0; bj < 2; ++bj) { const f32x4 xa = *(const f32x4*)(xin + off + bj * 128), xb = *(const f32x4*)(xin + off + bj * 128 + 4);
;                     const f32x4 ga = *(const f32x4*)(gpost + col0 + bj * 128), gb = *(const f32x4*)(gpost + col0 + bj * 128 + 4);
;                     const f32x4 v0 = xa + acc[ai][bj][m][0] * r1 * ga, v1 = xb + acc[ai][bj][m][1] * r1 * gb;
;                     *(f32x4*)(xout + off + bj * 128) = v0; *(f32x4*)(xout + off + bj * 128 + 4) = v1; acc[ai][bj][m][0] = v0; acc[ai][bj][m][1] = v1; }
;                 asm volatile("" ::: "memory"); }
	v_pk_mul_f32 v[30:31], v[30:31], v[250:251] op_sel_hi:[1,0]
	v_pk_mul_f32 v[32:33], v[32:33], v[250:251] op_sel_hi:[1,0]
	v_pk_mul_f32 v[26:27], v[26:27], v[250:251] op_sel_hi:[1,0]
	v_pk_mul_f32 v[28:29], v[28:29], v[250:251] op_sel_hi:[1,0]
	v_pk_mul_f32 v[22:23], v[22:23], v[250:251] op_sel_hi:[1,0]
	v_pk_mul_f32 v[24:25], v[24:25], v[250:251] op_sel_hi:[1,0]
	v_pk_mul_f32 v[18:19], v[18:19], v[250:251] op_sel_hi:[1,0]
	v_pk_mul_f32 v[20:21], v[20:21], v[250:251] op_sel_hi:[1,0]
	s_waitcnt vmcnt(12)
	v_pk_fma_f32 v[26:27], v[26:27], v[222:223], v[202:203]
	v_pk_fma_f32 v[28:29], v[28:29], v[224:225], v[204:205]
	v_pk_fma_f32 v[30:31], v[30:31], v[218:219], v[206:207]
	v_pk_fma_f32 v[32:33], v[32:33], v[220:221], v[208:209]
	v_pk_fma_f32 v[18:19], v[18:19], v[230:231], v[210:211]
	v_pk_fma_f32 v[20:21], v[20:21], v[232:233], v[212:213]
	v_pk_fma_f32 v[22:23], v[22:23], v[226:227], v[214:215]
	v_pk_fma_f32 v[24:25], v[24:25], v[228:229], v[216:217]
	global_store_dwordx4 v162, v[30:33], s[14:15]
	global_store_dwordx4 v162, v[26:29], s[14:15] offset:16
	global_store_dwordx4 v162, v[22:25], s[14:15] offset:512
	global_store_dwordx4 v162, v[18:21], s[14:15] offset:528
	s_waitcnt lgkmcnt(0)
	v_pk_mul_f32 v[14:15], v[14:15], v[192:193] op_sel_hi:[1,0]
	v_pk_mul_f32 v[16:17], v[16:17], v[192:193] op_sel_hi:[1,0]
	v_pk_mul_f32 v[10:11], v[10:11], v[192:193] op_sel_hi:[1,0]
	v_pk_mul_f32 v[12:13], v[12:13], v[192:193] op_sel_hi:[1,0]
	v_pk_mul_f32 v[6:7], v[6:7], v[192:193] op_sel_hi:[1,0]
	v_pk_mul_f32 v[8:9], v[8:9], v[192:193] op_sel_hi:[1,0]
	v_pk_mul_f32 v[2:3], v[2:3], v[192:193] op_sel_hi:[1,0]
	v_pk_mul_f32 v[4:5], v[4:5], v[192:193] op_sel_hi:[1,0]
	s_waitcnt vmcnt(8)
	v_pk_fma_f32 v[10:11], v[10:11], v[222:223], v[234:235]
	v_pk_fma_f32 v[12:13], v[12:13], v[224:225], v[236:237]
	v_pk_fma_f32 v[14:15], v[14:15], v[218:219], v[238:239]
	v_pk_fma_f32 v[16:17], v[16:17], v[220:221], v[240:241]
	v_pk_fma_f32 v[2:3], v[2:3], v[230:231], v[242:243]
	v_pk_fma_f32 v[4:5], v[4:5], v[232:233], v[244:245]
	v_pk_fma_f32 v[6:7], v[6:7], v[226:227], v[246:247]
	v_pk_fma_f32 v[8:9], v[8:9], v[228:229], v[248:249]
	global_store_dwordx4 v163, v[14:17], s[14:15]
	global_store_dwordx4 v163, v[10:13], s[14:15] offset:16
	global_store_dwordx4 v163, v[6:9], s[14:15] offset:512
	global_store_dwordx4 v163, v[2:5], s[14:15] offset:528
	v_add_u32_e32 v146, s54, v172
	v_ashrrev_i32_e32 v147, 31, v146
	v_add_u32_e32 v148, s54, v173
	v_ashrrev_i32_e32 v149, 31, v148
	v_add_u32_e32 v150, s54, v174
	v_ashrrev_i32_e32 v151, 31, v150
	v_add_u32_e32 v152, s54, v175
	v_ashrrev_i32_e32 v153, 31, v152
	v_add_u32_e32 v156, s54, v176
	v_ashrrev_i32_e32 v157, 31, v156
	v_add_u32_e32 v158, s54, v177
	v_ashrrev_i32_e32 v159, 31, v158
	v_add_u32_e32 v166, s54, v178
	v_ashrrev_i32_e32 v167, 31, v166
	s_cbranch_vccnz .LBB0_272
	v_mul_f32_e32 v154, v43, v43
	v_mul_f32_e32 v155, v45, v45
	v_fmac_f32_e32 v154, v42, v42
	v_fmac_f32_e32 v155, v44, v44
	v_add_f32_e32 v154, v154, v155
	v_mul_f32_e32 v155, v47, v47
	v_mul_f32_e32 v160, v49, v49
	v_fmac_f32_e32 v155, v46, v46
	v_fmac_f32_e32 v160, v48, v48
	v_add_f32_e32 v155, v155, v160
	v_add_f32_e32 v154, v154, v155
	v_mul_f32_e32 v155, v63, v63
	v_mul_f32_e32 v160, v65, v65
	v_fmac_f32_e32 v155, v62, v62
	v_fmac_f32_e32 v160, v64, v64
	v_add_f32_e32 v155, v155, v160
	v_add_f32_e32 v154, v154, v155
	v_mul_f32_e32 v155, v59, v59
	v_mul_f32_e32 v160, v61, v61
	v_fmac_f32_e32 v155, v58, v58
	v_fmac_f32_e32 v160, v60, v60
	v_add_f32_e32 v155, v155, v160
	v_add_f32_e32 v154, v154, v155
	ds_bpermute_b32 v155, v171, v154
	s_waitcnt lgkmcnt(0)
	v_add_f32_e32 v154, v154, v155
	v_mov_b32_e32 v155, v154
	s_nop 1
	v_permlane32_swap_b32_e32 v154, v155
	s_and_saveexec_b64 s[54:55], s[42:43]
	v_add_f32_e32 v154, v154, v155
	ds_write_b32 v191, v154
	s_or_b64 exec, exec, s[54:55]
	v_mul_f32_e32 v154, v67, v67
	v_mul_f32_e32 v155, v69, v69
	v_fmac_f32_e32 v154, v66, v66
	v_fmac_f32_e32 v155, v68, v68
	v_add_f32_e32 v154, v154, v155
	v_mul_f32_e32 v155, v71, v71
	v_mul_f32_e32 v160, v73, v73
	v_fmac_f32_e32 v155, v70, v70
	v_fmac_f32_e32 v160, v72, v72
	v_add_f32_e32 v155, v155, v160
	v_add_f32_e32 v154, v154, v155
	v_mul_f32_e32 v155, v87, v87
	v_mul_f32_e32 v160, v89, v89
	v_fmac_f32_e32 v155, v86, v86
	v_fmac_f32_e32 v160, v88, v88
	v_add_f32_e32 v155, v155, v160
	v_add_f32_e32 v154, v154, v155
	v_mul_f32_e32 v155, v83, v83
	v_mul_f32_e32 v160, v85, v85
	v_fmac_f32_e32 v155, v82, v82
	v_fmac_f32_e32 v160, v84, v84
	v_add_f32_e32 v155, v155, v160
	v_add_f32_e32 v154, v154, v155
	ds_bpermute_b32 v155, v171, v154
	s_waitcnt lgkmcnt(0)
	v_add_f32_e32 v154, v154, v155
	v_mov_b32_e32 v155, v154
	s_nop 1
	v_permlane32_swap_b32_e32 v154, v155
	s_and_saveexec_b64 s[54:55], s[42:43]
	v_add_f32_e32 v154, v154, v155
	ds_write_b32 v191, v154 offset:256
	s_or_b64 exec, exec, s[54:55]
	v_mul_f32_e32 v154, v99, v99
	v_mul_f32_e32 v155, v101, v101
	v_fmac_f32_e32 v154, v98, v98
	v_fmac_f32_e32 v155, v100, v100
	v_add_f32_e32 v154, v154, v155
	v_mul_f32_e32 v155, v103, v103
	v_mul_f32_e32 v160, v105, v105
	v_fmac_f32_e32 v155, v102, v102
	v_fmac_f32_e32 v160, v104, v104
	v_add_f32_e32 v155, v155, v160
	v_add_f32_e32 v154, v154, v155
	v_mul_f32_e32 v155, v111, v111
	v_mul_f32_e32 v160, v113, v113
	v_fmac_f32_e32 v155, v110, v110
	v_fmac_f32_e32 v160, v112, v112
	v_add_f32_e32 v155, v155, v160
	v_add_f32_e32 v154, v154, v155
	v_mul_f32_e32 v155, v107, v107
	v_mul_f32_e32 v160, v109, v109
	v_fmac_f32_e32 v155, v106, v106
	v_fmac_f32_e32 v160, v108, v108
	v_add_f32_e32 v155, v155, v160
	v_add_f32_e32 v154, v154, v155
	ds_bpermute_b32 v155, v171, v154
	s_waitcnt lgkmcnt(0)
; __device__ __forceinline__ float swap_add(float v) { auto rr = __builtin_amdgcn_permlane32_swap(__float_as_uint(v), __float_as_uint(v), false, false); return __uint_as_float(rr[0]) + __uint_as_float(rr[1]); }
;     __device__ __forceinline__ void exchange(const f32x4 (&acc)[2][2][4][2], const Unit& u, int e, int wr, int wc, int fr, int fq) const {
;     ...
; #pragma unroll
;         for (int ai = 0; ai < 2; ++ai)
; #pragma unroll
;             for (int m = 0; m < 4; ++m) { float q = 0.f;
; #pragma unroll
;                 for (int bj = 0; bj < 2; ++bj)
; #pragma unroll
;                     for (int n = 0; n < 2; ++n) { const f32x4 v = acc[ai][bj][m][n]; q += (v[0] * v[0] + v[1] * v[1]) + (v[2] * v[2] + v[3] * v[3]); }
;                 q += __int_as_float(__builtin_amdgcn_ds_bpermute((lid ^ 16) << 2, __float_as_int(q))); q = swap_add(q);
;                 if (fq == 0) P[(ai * 128 + wr * 64 + m * 16 + fr) * 4 + wc] = q; }
;         __syncthreads();
;         float* xb = xbuf + (size_t)e * T * 4 + (size_t)u.pm * 256 * 4; unsigned* c = cnt + (e * 64 + u.pm) * 64;
;         if (tid < 256) { const float tot = (P[tid * 4] + P[tid * 4 + 1]) + (P[tid * 4 + 2] + P[tid * 4 + 3]);
;             __hip_atomic_store(xb + tid * 4 + u.pn, tot, __ATOMIC_RELAXED, __HIP_MEMORY_SCOPE_AGENT); }
	v_add_f32_e32 v154, v154, v155
	v_mov_b32_e32 v155, v154
	s_nop 1
	v_permlane32_swap_b32_e32 v154, v155
	s_and_saveexec_b64 s[54:55], s[42:43]
	v_add_f32_e32 v154, v154, v155
	ds_write_b32 v191, v154 offset:512
	s_or_b64 exec, exec, s[54:55]
	v_mul_f32_e32 v154, v123, v123
	v_mul_f32_e32 v155, v125, v125
	v_fmac_f32_e32 v154, v122, v122
	v_fmac_f32_e32 v155, v124, v124
	v_add_f32_e32 v154, v154, v155
	v_mul_f32_e32 v155, v127, v127
	v_mul_f32_e32 v160, v129, v129
	v_fmac_f32_e32 v155, v126, v126
	v_fmac_f32_e32 v160, v128, v128
	v_add_f32_e32 v155, v155, v160
	v_add_f32_e32 v154, v154, v155
	v_mul_f32_e32 v155, v119, v119
	v_mul_f32_e32 v160, v121, v121
	v_fmac_f32_e32 v155, v118, v118
	v_fmac_f32_e32 v160, v120, v120
	v_add_f32_e32 v155, v155, v160
	v_add_f32_e32 v154, v154, v155
	v_mul_f32_e32 v155, v115, v115
	v_mul_f32_e32 v160, v117, v117
	v_fmac_f32_e32 v155, v114, v114
	v_fmac_f32_e32 v160, v116, v116
	v_add_f32_e32 v155, v155, v160
	v_add_f32_e32 v154, v154, v155
	ds_bpermute_b32 v155, v171, v154
	s_waitcnt lgkmcnt(0)
	v_add_f32_e32 v154, v154, v155
	v_mov_b32_e32 v155, v154
	s_nop 1
	v_permlane32_swap_b32_e32 v154, v155
	s_and_saveexec_b64 s[54:55], s[42:43]
	v_add_f32_e32 v154, v154, v155
	ds_write_b32 v191, v154 offset:768
	s_or_b64 exec, exec, s[54:55]
	v_mul_f32_e32 v154, v95, v95
	v_mul_f32_e32 v155, v97, v97
	v_fmac_f32_e32 v154, v94, v94
	v_fmac_f32_e32 v155, v96, v96
	v_add_f32_e32 v154, v154, v155
	v_mul_f32_e32 v155, v91, v91
	v_mul_f32_e32 v160, v93, v93
	v_fmac_f32_e32 v155, v90, v90
	v_fmac_f32_e32 v160, v92, v92
	v_add_f32_e32 v155, v155, v160
	v_add_f32_e32 v154, v154, v155
	v_mul_f32_e32 v155, v79, v79
	v_mul_f32_e32 v160, v81, v81
	v_fmac_f32_e32 v155, v78, v78
	v_fmac_f32_e32 v160, v80, v80
	v_add_f32_e32 v155, v155, v160
	v_add_f32_e32 v154, v154, v155
	v_mul_f32_e32 v155, v75, v75
	v_mul_f32_e32 v160, v77, v77
	v_fmac_f32_e32 v155, v74, v74
	v_fmac_f32_e32 v160, v76, v76
	v_add_f32_e32 v155, v155, v160
	v_add_f32_e32 v154, v154, v155
	ds_bpermute_b32 v155, v171, v154
	s_waitcnt lgkmcnt(0)
	v_add_f32_e32 v154, v154, v155
	v_mov_b32_e32 v155, v154
	s_nop 1
	v_permlane32_swap_b32_e32 v154, v155
	s_and_saveexec_b64 s[54:55], s[42:43]
	v_add_f32_e32 v154, v154, v155
	ds_write_b32 v191, v154 offset:2048
	s_or_b64 exec, exec, s[54:55]
	v_mul_f32_e32 v154, v55, v55
	v_mul_f32_e32 v155, v57, v57
	v_fmac_f32_e32 v154, v54, v54
	v_fmac_f32_e32 v155, v56, v56
	v_add_f32_e32 v154, v154, v155
	v_mul_f32_e32 v155, v51, v51
	v_mul_f32_e32 v160, v53, v53
	v_fmac_f32_e32 v155, v50, v50
	v_fmac_f32_e32 v160, v52, v52
	v_add_f32_e32 v155, v155, v160
	v_add_f32_e32 v154, v154, v155
	v_mul_f32_e32 v155, v39, v39
	v_mul_f32_e32 v160, v41, v41
	v_fmac_f32_e32 v155, v38, v38
	v_fmac_f32_e32 v160, v40, v40
	v_add_f32_e32 v155, v155, v160
	v_add_f32_e32 v154, v154, v155
	v_mul_f32_e32 v155, v35, v35
	v_mul_f32_e32 v160, v37, v37
	v_fmac_f32_e32 v155, v34, v34
	v_fmac_f32_e32 v160, v36, v36
	v_add_f32_e32 v155, v155, v160
	v_add_f32_e32 v154, v154, v155
	ds_bpermute_b32 v155, v171, v154
	s_waitcnt lgkmcnt(0)
	v_add_f32_e32 v154, v154, v155
	v_mov_b32_e32 v155, v154
	s_nop 1
	v_permlane32_swap_b32_e32 v154, v155
	s_and_saveexec_b64 s[54:55], s[42:43]
	v_add_f32_e32 v154, v154, v155
	ds_write_b32 v191, v154 offset:2304
	s_or_b64 exec, exec, s[54:55]
	v_mul_f32_e32 v154, v31, v31
	v_mul_f32_e32 v155, v33, v33
	v_fmac_f32_e32 v154, v30, v30
	v_fmac_f32_e32 v155, v32, v32
	v_add_f32_e32 v154, v154, v155
	v_mul_f32_e32 v155, v27, v27
	v_mul_f32_e32 v160, v29, v29
	v_fmac_f32_e32 v155, v26, v26
	v_fmac_f32_e32 v160, v28, v28
	v_add_f32_e32 v155, v155, v160
	v_add_f32_e32 v154, v154, v155
	v_mul_f32_e32 v155, v23, v23
	v_mul_f32_e32 v160, v25, v25
	v_fmac_f32_e32 v155, v22, v22
	v_fmac_f32_e32 v160, v24, v24
	v_add_f32_e32 v155, v155, v160
	v_add_f32_e32 v154, v154, v155
	v_mul_f32_e32 v155, v19, v19
	v_mul_f32_e32 v160, v21, v21
	v_fmac_f32_e32 v155, v18, v18
	v_fmac_f32_e32 v160, v20, v20
	v_add_f32_e32 v155, v155, v160
	v_add_f32_e32 v154, v154, v155
	ds_bpermute_b32 v155, v171, v154
	s_waitcnt lgkmcnt(0)
	v_add_f32_e32 v154, v154, v155
	v_mov_b32_e32 v155, v154
	s_nop 1
	v_permlane32_swap_b32_e32 v154, v155
	s_and_saveexec_b64 s[54:55], s[42:43]
	v_add_f32_e32 v154, v154, v155
	ds_write_b32 v191, v154 offset:2560
	s_or_b64 exec, exec, s[54:55]
	v_mul_f32_e32 v154, v15, v15
	v_mul_f32_e32 v155, v17, v17
	v_fmac_f32_e32 v154, v14, v14
	v_fmac_f32_e32 v155, v16, v16
	v_add_f32_e32 v154, v154, v155
	v_mul_f32_e32 v155, v11, v11
	v_mul_f32_e32 v160, v13, v13
	v_fmac_f32_e32 v155, v10, v10
	v_fmac_f32_e32 v160, v12, v12
	v_add_f32_e32 v155, v155, v160
	v_add_f32_e32 v154, v154, v155
	v_mul_f32_e32 v155, v7, v7
	v_mul_f32_e32 v160, v9, v9
	v_fmac_f32_e32 v155, v6, v6
	v_fmac_f32_e32 v160, v8, v8
	v_add_f32_e32 v155, v155, v160
	v_add_f32_e32 v154, v154, v155
	v_mul_f32_e32 v155, v3, v3
	v_mul_f32_e32 v160, v5, v5
	v_fmac_f32_e32 v155, v2, v2
	v_fmac_f32_e32 v160, v4, v4
	v_add_f32_e32 v155, v155, v160
	v_add_f32_e32 v154, v154, v155
	ds_bpermute_b32 v155, v171, v154
	s_waitcnt lgkmcnt(0)
	v_add_f32_e32 v154, v154, v155
	v_mov_b32_e32 v155, v154
	s_nop 1
	v_permlane32_swap_b32_e32 v154, v155
	s_and_saveexec_b64 s[54:55], s[42:43]
	v_add_f32_e32 v154, v154, v155
	ds_write_b32 v191, v154 offset:2816
	s_or_b64 exec, exec, s[54:55]
	s_add_u32 s12, s97, s12
	s_addc_u32 s13, s72, s13
	v_lshl_add_u64 v[154:155], v[136:137], 2, s[12:13]
	s_waitcnt lgkmcnt(0)
	s_barrier
	s_and_saveexec_b64 s[12:13], s[44:45]
	s_cbranch_execz .LBB0_254
	ds_read_b128 v[202:205], v179
	s_ashr_i32 s77, s76, 31
	v_lshl_add_u64 v[162:163], s[76:77], 2, v[154:155]
	s_waitcnt lgkmcnt(0)
	v_mov_b32_e32 v160, v203
	v_mov_b32_e32 v161, v204
	v_mov_b32_e32 v203, v205
	v_pk_add_f32 v[160:161], v[160:161], v[202:203]
	s_nop 0
	v_pk_add_f32 v[160:161], v[160:161], v[160:161] op_sel:[0,1] op_sel_hi:[1,0]
	global_store_dword v[162:163], v160, off sc1
